# P3 qknorm: second-round kv_raw loads issued with the first batch (one HBM round trip per token); k gains half in regs half via LDS staged once per wave
# baseline (speedup 1.0000x reference)
.LBB0_272:
	s_cmp_lt_i32 s98, 4
	s_cselect_b64 s[0:1], -1, 0
	s_cmp_gt_i32 s99, 3
	s_cselect_b64 s[4:5], -1, 0
	s_and_b64 s[0:1], s[0:1], s[4:5]
	s_andn2_b64 vcc, exec, s[0:1]
	s_cbranch_vccnz .LBB0_288
	v_mbcnt_hi_u32_b32 v2, -1, v147
	v_readlane_b32 s0, v255, 3
	v_mov_b32_e32 v3, v2
	s_cmpk_gt_i32 s0, 0x7fff
	v_readlane_b32 s1, v255, 4
	s_cbranch_scc1 .LBB0_276
	v_and_b32_e32 v7, 3, v3
	v_ashrrev_i32_e32 v9, 2, v3
	v_lshlrev_b32_e32 v64, 4, v3
	v_lshlrev_b32_e32 v3, 6, v3
	s_movk_i32 s0, 0xc0
	v_and_b32_e32 v8, 64, v3
	v_and_b32_e32 v3, 64, v2
	v_mul_lo_u32 v10, v9, s0
	v_lshlrev_b32_e32 v62, 5, v7
	v_lshlrev_b32_e32 v6, 3, v7
	v_lshlrev_b32_e32 v11, 7, v7
	v_lshlrev_b32_e32 v12, 4, v7
	v_cmp_gt_u32_e64 s[0:1], 2, v7
	v_cmp_lt_u32_e64 s[4:5], 1, v7
	v_add_u32_e32 v3, 64, v3
	v_xor_b32_e32 v7, 1, v2
	v_cmp_lt_i32_e32 vcc, v7, v3
	s_add_u32 s22, s96, 0x7a00000
	s_addc_u32 s23, s97, 0
	v_cndmask_b32_e32 v7, v2, v7, vcc
	v_lshlrev_b32_e32 v63, 2, v7
	v_xor_b32_e32 v7, 2, v2
	v_cmp_lt_i32_e32 vcc, v7, v3
	s_add_u32 s24, s96, 0x7c00000
	v_readlane_b32 s7, v255, 2
	v_cndmask_b32_e32 v7, v2, v7, vcc
	v_lshlrev_b32_e32 v108, 2, v7
	v_xor_b32_e32 v7, 4, v2
	v_cmp_lt_i32_e32 vcc, v7, v3
	s_addc_u32 s25, s97, 0
	s_lshl_b32 s6, s2, 8
	v_cndmask_b32_e32 v7, v2, v7, vcc
	v_lshlrev_b32_e32 v109, 2, v7
	v_xor_b32_e32 v7, 8, v2
	v_cmp_lt_i32_e32 vcc, v7, v3
	s_lshl_b32 s7, s7, 5
	s_add_i32 s26, s6, s7
	v_cndmask_b32_e32 v7, v2, v7, vcc
	v_lshlrev_b32_e32 v110, 2, v7
	v_xor_b32_e32 v7, 16, v2
	v_cmp_lt_i32_e32 vcc, v7, v3
	v_readlane_b32 s6, v255, 3
	v_mov_b32_e32 v65, 0
	v_cndmask_b32_e32 v7, v2, v7, vcc
	v_lshlrev_b32_e32 v111, 2, v7
	v_xor_b32_e32 v7, 32, v2
	v_cmp_lt_i32_e32 vcc, v7, v3
	v_readlane_b32 s7, v255, 4
	s_mov_b32 s20, s6
	v_cndmask_b32_e32 v2, v2, v7, vcc
	s_ashr_i32 s21, s6, 31
	v_lshlrev_b32_e32 v112, 2, v2
	s_lshl_b64 s[6:7], s[20:21], 13
	v_lshl_or_b32 v2, v9, 9, v11
	v_mov_b32_e32 v3, v65
	v_lshl_add_u64 v[66:67], s[6:7], 0, v[2:3]
	v_or_b32_e32 v2, v10, v6
	v_mov_b32_e32 v3, 0x100
	v_mov_b32_e32 v7, 0x1800
	v_lshl_add_u32 v2, v2, 1, v3
	v_mov_b32_e32 v3, v65
	v_mad_i64_i32 v[70:71], s[10:11], s20, v7, v[2:3]
	v_mov_b32_e32 v2, 0x1a00
	v_add_lshl_u32 v4, v10, v62, 1
	v_mov_b32_e32 v5, v65
	s_mul_hi_i32 s12, s20, 0x1a00
	s_mul_i32 s13, s20, 0x1a00
	v_mad_i64_i32 v[72:73], s[10:11], s20, v2, v[64:65]
	v_lshl_or_b32 v64, v9, 7, v12
	s_mov_b32 s18, s20
	s_ashr_i32 s47, s46, 31
	v_mad_i64_i32 v[68:69], s[8:9], s20, v7, v[4:5]
	v_or_b32_e32 v74, s13, v12
	v_mov_b32_e32 v75, s12
	v_mad_i64_i32 v[76:77], s[12:13], s20, v2, v[64:65]
	v_writelane_b32 v255, s18, 3
	s_lshl_b32 s27, s3, 8
	s_lshl_b64 s[6:7], s[46:47], 13
	s_mul_hi_i32 s9, s46, 0x1800
	s_mul_i32 s8, s46, 0x1800
	s_mul_hi_i32 s11, s46, 0x1a00
	s_mul_i32 s10, s46, 0x1a00
	s_mov_b32 s28, 0x11000000
	s_mov_b64 s[12:13], 0x1e000000
	s_mov_b32 s29, 0x1e000000
	s_mov_b64 s[14:15], 0x2a000000
	s_mov_b32 s30, 0x2a000000
	s_mov_b64 s[16:17], 0x2a000040
	v_mov_b32_e32 v113, 0x358637bd
	v_lshlrev_b32_e32 v64, 2, v62
	v_lshlrev_b32_e32 v78, 2, v6
	v_mov_b32_e32 v79, v65
	v_lshlrev_b32_e32 v80, 2, v8
	v_mov_b32_e32 v81, v65
	v_writelane_b32 v255, s19, 4
	s_mov_b32 s31, s20
	v_lshl_add_u64 v[186:187], s[76:77], 0, v[80:81]
	global_load_dwordx4 v[190:193], v[186:187], off
	global_load_dwordx4 v[194:197], v[186:187], off offset:16
	global_load_dwordx4 v[198:201], v[186:187], off offset:32
	global_load_dwordx4 v[202:205], v[186:187], off offset:48
	global_load_dwordx4 v[206:209], v[186:187], off offset:64
	global_load_dwordx4 v[210:213], v[186:187], off offset:80
	global_load_dwordx4 v[214:217], v[186:187], off offset:96
	global_load_dwordx4 v[218:221], v[186:187], off offset:112
	global_load_dwordx4 v[222:225], v[186:187], off offset:128
	global_load_dwordx4 v[226:229], v[186:187], off offset:144
	global_load_dwordx4 v[230:233], v[186:187], off offset:160
	global_load_dwordx4 v[234:237], v[186:187], off offset:176
	global_load_dwordx4 v[238:241], v[186:187], off offset:192
	global_load_dwordx4 v[242:245], v[186:187], off offset:208
	global_load_dwordx4 v[246:249], v[186:187], off offset:224
	global_load_dwordx4 v[250:253], v[186:187], off offset:240
	v_mbcnt_lo_u32_b32 v188, -1, 0
	v_mbcnt_hi_u32_b32 v188, -1, v188
	v_readlane_b32 s40, v255, 2
	s_lshl_b32 s40, s40, 14
	v_lshl_add_u32 v188, v188, 4, s40
	s_waitcnt vmcnt(0)
	ds_write_b128 v188, v[222:225]
	ds_write_b128 v188, v[226:229] offset:1024
	ds_write_b128 v188, v[230:233] offset:2048
	ds_write_b128 v188, v[234:237] offset:3072
	ds_write_b128 v188, v[238:241] offset:4096
	ds_write_b128 v188, v[242:245] offset:5120
	ds_write_b128 v188, v[246:249] offset:6144
	ds_write_b128 v188, v[250:253] offset:7168
	s_waitcnt lgkmcnt(0)
.LBB0_275:
	v_lshl_add_u64 v[6:7], s[96:97], 0, v[72:73]
	v_lshl_add_u64 v[2:3], s[96:97], 0, v[68:69]
	v_add_co_u32_e32 v6, vcc, 0x11000000, v6
	s_mov_b64 s[20:21], s[62:63]
	s_mov_b64 s[18:19], s[76:77]
	v_lshl_add_u64 v[4:5], v[2:3], 0, s[12:13]
	v_addc_co_u32_e32 v7, vcc, 0, v7, vcc
	global_load_dwordx4 v[48:51], v[4:5], off offset:32
	global_load_dwordx4 v[52:55], v[4:5], off offset:48
	global_load_dwordx4 v[56:59], v[6:7], off
	global_load_dwordx4 v[86:89], v[4:5], off offset:16
	v_add_co_u32_e32 v84, vcc, 0x1e000000, v2
	v_lshl_add_u64 v[4:5], s[96:97], 0, v[74:75]
	s_nop 0
	v_addc_co_u32_e32 v85, vcc, 0, v3, vcc
	global_load_dwordx4 v[90:93], v[84:85], off
	v_add_co_u32_e32 v44, vcc, s28, v4
	v_lshl_add_u64 v[42:43], s[96:97], 0, v[66:67]
	s_nop 0
	v_addc_co_u32_e32 v45, vcc, 0, v5, vcc
	v_add_co_u32_e32 v82, vcc, s30, v42
	v_lshl_add_u64 v[2:3], s[96:97], 0, v[70:71]
	s_nop 0
	v_addc_co_u32_e32 v83, vcc, 0, v43, vcc
	v_add_co_u32_e32 v100, vcc, s29, v2
	s_and_b32 s33, s26, 0x7ffe0
	s_nop 0
	v_addc_co_u32_e32 v101, vcc, 0, v3, vcc
	global_load_dwordx4 v[34:37], v[100:101], off
	global_load_dwordx4 v[38:41], v[100:101], off offset:64
	s_lshl_b32 s33, s33, 2
	s_add_u32 s34, s22, s33
	v_mov_b32_e32 v8, v62
	s_addc_u32 s35, s23, 0
	s_add_u32 s38, s24, s33
	v_lshl_add_u64 v[46:47], v[42:43], 0, s[14:15]
	s_addc_u32 s39, s25, 0
	global_load_dwordx4 v[30:33], v[6:7], off offset:1024
	global_load_dwordx4 v[26:29], v[44:45], off offset:2048
	global_load_dwordx4 v[18:21], v[46:47], off offset:48
	global_load_dwordx4 v[22:25], v[46:47], off offset:32
	global_load_dwordx4 v[10:13], v8, s[34:35]
	global_load_dwordx4 v[2:5], v8, s[34:35] offset:16
	global_load_dwordx4 v[14:17], v8, s[38:39]
	s_nop 0
	global_load_dwordx4 v[6:9], v8, s[38:39] offset:16
	v_lshl_add_u64 v[42:43], v[42:43], 0, s[16:17]
	v_lshl_add_u64 v[142:143], s[20:21], 0, v[78:79]
	global_load_dwordx4 v[222:225], v[44:45], off offset:2112
	global_load_dwordx4 v[226:229], v[46:47], off offset:16
	global_load_dwordx4 v[230:233], v[82:83], off
	global_load_dwordx4 v[234:237], v[82:83], off offset:64
	global_load_dwordx4 v[238:241], v[42:43], off offset:48
	global_load_dwordx4 v[242:245], v[42:43], off offset:32
	global_load_dwordx4 v[246:249], v[42:43], off offset:16
	s_waitcnt vmcnt(0)
	v_lshlrev_b32_e32 v148, 16, v49
	v_and_b32_e32 v149, 0xffff0000, v49
	v_and_b32_e32 v49, 0xffff0000, v56
	v_lshlrev_b32_e32 v145, 16, v48
	v_and_b32_e32 v146, 0xffff0000, v48
	v_lshlrev_b32_e32 v48, 16, v56
	v_mul_f32_e32 v49, v49, v49
	v_lshlrev_b32_e32 v150, 16, v50
	v_and_b32_e32 v151, 0xffff0000, v50
	v_lshlrev_b32_e32 v50, 16, v57
	v_fmac_f32_e32 v49, v48, v48
	v_lshlrev_b32_e32 v152, 16, v51
	v_and_b32_e32 v153, 0xffff0000, v51
	v_and_b32_e32 v51, 0xffff0000, v57
	v_fmac_f32_e32 v49, v50, v50
	v_lshlrev_b32_e32 v154, 16, v52
	v_and_b32_e32 v155, 0xffff0000, v52
	v_lshlrev_b32_e32 v52, 16, v58
	v_fmac_f32_e32 v49, v51, v51
	v_lshlrev_b32_e32 v156, 16, v53
	v_and_b32_e32 v157, 0xffff0000, v53
	v_and_b32_e32 v53, 0xffff0000, v58
	v_fmac_f32_e32 v49, v52, v52
	v_lshlrev_b32_e32 v158, 16, v54
	v_and_b32_e32 v159, 0xffff0000, v54
	v_lshlrev_b32_e32 v54, 16, v59
	v_fmac_f32_e32 v49, v53, v53
	v_lshlrev_b32_e32 v160, 16, v55
	v_and_b32_e32 v161, 0xffff0000, v55
	v_and_b32_e32 v55, 0xffff0000, v59
	v_fmac_f32_e32 v49, v54, v54
	v_fmac_f32_e32 v49, v55, v55
	ds_bpermute_b32 v48, v63, v49
	v_lshlrev_b32_e32 v162, 16, v86
	v_and_b32_e32 v163, 0xffff0000, v86
	v_lshlrev_b32_e32 v164, 16, v87
	v_and_b32_e32 v165, 0xffff0000, v87
	s_waitcnt lgkmcnt(0)
	v_add_f32_e32 v48, v49, v48
	ds_bpermute_b32 v49, v108, v48
	v_lshlrev_b32_e32 v166, 16, v88
	v_and_b32_e32 v167, 0xffff0000, v88
	v_lshlrev_b32_e32 v168, 16, v89
	v_and_b32_e32 v169, 0xffff0000, v89
	s_waitcnt lgkmcnt(0)
	v_add_f32_e32 v48, v48, v49
	ds_bpermute_b32 v49, v109, v48
	v_lshlrev_b32_e32 v170, 16, v90
	v_and_b32_e32 v171, 0xffff0000, v90
	v_lshlrev_b32_e32 v172, 16, v91
	v_and_b32_e32 v173, 0xffff0000, v91
	s_waitcnt lgkmcnt(0)
	v_add_f32_e32 v48, v48, v49
	ds_bpermute_b32 v49, v110, v48
	v_lshlrev_b32_e32 v174, 16, v92
	v_and_b32_e32 v175, 0xffff0000, v92
	v_lshlrev_b32_e32 v176, 16, v93
	v_and_b32_e32 v177, 0xffff0000, v93
	s_waitcnt lgkmcnt(0)
	v_add_f32_e32 v48, v48, v49
	ds_bpermute_b32 v49, v111, v48
	v_mul_f32_e32 v52, v171, v171
	v_fmac_f32_e32 v52, v170, v170
	v_fmac_f32_e32 v52, v172, v172
	v_fmac_f32_e32 v52, v173, v173
	s_waitcnt lgkmcnt(0)
	v_add_f32_e32 v54, v48, v49
	v_lshl_add_u64 v[48:49], s[20:21], 0, v[64:65]
	flat_load_dwordx4 v[86:89], v[48:49]
	flat_load_dwordx4 v[90:93], v[48:49] offset:16
	flat_load_dwordx4 v[114:117], v[48:49] offset:32
	flat_load_dwordx4 v[118:121], v[48:49] offset:48
	flat_load_dwordx4 v[122:125], v[48:49] offset:64
	flat_load_dwordx4 v[126:129], v[48:49] offset:80
	flat_load_dwordx4 v[130:133], v[48:49] offset:96
	flat_load_dwordx4 v[134:137], v[48:49] offset:112
	v_fmac_f32_e32 v52, v174, v174
	v_fmac_f32_e32 v52, v175, v175
	v_fmac_f32_e32 v52, v176, v176
	v_fmac_f32_e32 v52, v177, v177
	v_fmac_f32_e32 v52, v162, v162
	v_fmac_f32_e32 v52, v163, v163
	v_fmac_f32_e32 v52, v164, v164
	v_fmac_f32_e32 v52, v165, v165
	v_fmac_f32_e32 v52, v166, v166
	v_fmac_f32_e32 v52, v167, v167
	v_fmac_f32_e32 v52, v168, v168
	v_fmac_f32_e32 v52, v169, v169
	v_fmac_f32_e32 v52, v145, v145
	v_fmac_f32_e32 v52, v146, v146
	v_fmac_f32_e32 v52, v148, v148
	v_fmac_f32_e32 v52, v149, v149
	v_fmac_f32_e32 v52, v150, v150
	v_fmac_f32_e32 v52, v151, v151
	v_fmac_f32_e32 v52, v152, v152
	v_fmac_f32_e32 v52, v153, v153
	v_fmac_f32_e32 v52, v154, v154
	v_fmac_f32_e32 v52, v155, v155
	v_lshlrev_b32_e32 v99, 16, v41
	v_and_b32_e32 v103, 0xffff0000, v41
	v_fmac_f32_e32 v52, v156, v156
	v_lshlrev_b32_e32 v98, 16, v37
	v_and_b32_e32 v102, 0xffff0000, v37
	v_mov_b32_e32 v50, v103
	v_mov_b32_e32 v51, v99
	v_and_b32_e32 v105, 0xffff0000, v40
	v_and_b32_e32 v104, 0xffff0000, v36
	v_fmac_f32_e32 v52, v157, v157
	v_mov_b32_e32 v48, v102
	v_mov_b32_e32 v49, v98
	v_pk_mul_f32 v[50:51], v[50:51], v[50:51]
	v_lshlrev_b32_e32 v97, 16, v40
	v_lshlrev_b32_e32 v96, 16, v36
	v_pk_mul_f32 v[36:37], v[104:105], v[104:105]
	v_lshlrev_b32_e32 v95, 16, v39
	v_lshlrev_b32_e32 v94, 16, v35
	v_fmac_f32_e32 v52, v158, v158
	v_pk_fma_f32 v[48:49], v[48:49], v[48:49], v[50:51]
	v_pk_mul_f32 v[50:51], v[96:97], v[96:97]
	v_add_f32_e32 v40, v36, v37
	v_pk_mul_f32 v[36:37], v[94:95], v[94:95]
	v_and_b32_e32 v107, 0xffff0000, v39
	v_and_b32_e32 v106, 0xffff0000, v35
	v_fmac_f32_e32 v52, v159, v159
	v_add_f32_e32 v41, v50, v51
	v_add_f32_e32 v50, v36, v37
	v_pk_mul_f32 v[36:37], v[106:107], v[106:107]
	v_lshlrev_b32_e32 v139, 16, v38
	v_lshlrev_b32_e32 v138, 16, v34
	v_fmac_f32_e32 v52, v160, v160
	v_add_f32_e32 v39, v36, v37
	v_pk_mul_f32 v[36:37], v[138:139], v[138:139]
	v_fmac_f32_e32 v52, v161, v161
	v_add_f32_e32 v35, v36, v37
	v_and_b32_e32 v141, 0xffff0000, v38
	v_and_b32_e32 v140, 0xffff0000, v34
	v_add_f32_e32 v36, v35, v52
	v_pk_mul_f32 v[34:35], v[140:141], v[140:141]
	ds_bpermute_b32 v55, v112, v54
	v_add_f32_e32 v34, v34, v35
	v_add_f32_e32 v34, v34, v36
	v_add_f32_e32 v34, v50, v34
	v_add_f32_e32 v34, v39, v34
	v_add_f32_e32 v34, v41, v34
	v_add_f32_e32 v34, v40, v34
	v_add_f32_e32 v34, v49, v34
	v_add_f32_e32 v34, v48, v34
	ds_bpermute_b32 v35, v63, v34
	s_waitcnt lgkmcnt(0)
	v_add_f32_e32 v36, v54, v55
	v_fmamk_f32 v36, v36, 0x3b000000, v113
	v_rsq_f32_e32 v144, v36
	v_mov_b32_e32 v58, v222
	v_mov_b32_e32 v59, v223
	v_mov_b32_e32 v60, v224
	v_mov_b32_e32 v61, v225
	v_mov_b32_e32 v50, v226
	v_mov_b32_e32 v51, v227
	v_mov_b32_e32 v52, v228
	v_mov_b32_e32 v53, v229
	v_add_f32_e32 v38, v34, v35
	ds_bpermute_b32 v39, v108, v38
	v_mov_b32_e32 v54, v230
	v_mov_b32_e32 v55, v231
	v_mov_b32_e32 v56, v232
	v_mov_b32_e32 v57, v233
	v_mov_b32_e32 v46, v234
	v_mov_b32_e32 v47, v235
	v_mov_b32_e32 v48, v236
	v_mov_b32_e32 v49, v237
	v_mov_b32_e32 v34, v238
	v_mov_b32_e32 v35, v239
	v_mov_b32_e32 v36, v240
	v_mov_b32_e32 v37, v241
	s_waitcnt lgkmcnt(0)
	v_add_f32_e32 v38, v38, v39
	v_mul_f32_e32 v38, v144, v38
	v_mul_f32_e32 v38, v144, v38
	v_fmamk_f32 v38, v38, 0x3baaaaab, v113
	v_rsq_f32_e32 v178, v38
	v_mov_b32_e32 v38, v242
	v_mov_b32_e32 v39, v243
	v_mov_b32_e32 v40, v244
	v_mov_b32_e32 v41, v245
	s_nop 0
	v_mov_b32_e32 v42, v246
	v_mov_b32_e32 v43, v247
	v_mov_b32_e32 v44, v248
	v_mov_b32_e32 v45, v249
	v_mul_f32_e32 v144, v144, v178
	v_mul_f32_e32 v144, 0x3dd53b95, v144
	s_waitcnt vmcnt(0)
	v_mul_f32_e32 v86, v86, v144
	v_mul_f32_e32 v87, v87, v144
	v_mul_f32_e32 v88, v88, v144
	v_mul_f32_e32 v89, v89, v144
	v_mul_f32_e32 v86, v86, v170
	v_mul_f32_e32 v87, v87, v171
	v_mul_f32_e32 v88, v88, v172
	v_mul_f32_e32 v89, v89, v173
	v_mul_f32_e32 v90, v90, v144
	v_mul_f32_e32 v91, v91, v144
	v_mul_f32_e32 v92, v92, v144
	v_mul_f32_e32 v93, v93, v144
	v_mul_f32_e32 v90, v90, v174
	v_mul_f32_e32 v91, v91, v175
	v_mul_f32_e32 v92, v92, v176
	v_mul_f32_e32 v93, v93, v177
	v_mul_f32_e32 v114, v114, v144
	v_mul_f32_e32 v115, v115, v144
	v_mul_f32_e32 v116, v116, v144
	v_mul_f32_e32 v117, v117, v144
	v_mul_f32_e32 v118, v118, v144
	v_mul_f32_e32 v119, v119, v144
	v_mul_f32_e32 v120, v120, v144
	v_mul_f32_e32 v121, v121, v144
	v_cvt_pk_bf16_f32 v86, v86, v87
	v_cvt_pk_bf16_f32 v87, v88, v89
	v_cvt_pk_bf16_f32 v88, v90, v91
	v_cvt_pk_bf16_f32 v89, v92, v93
	v_mul_f32_e32 v114, v114, v162
	v_mul_f32_e32 v115, v115, v163
	v_mul_f32_e32 v116, v116, v164
	v_mul_f32_e32 v117, v117, v165
	v_mul_f32_e32 v118, v118, v166
	v_mul_f32_e32 v119, v119, v167
	v_mul_f32_e32 v120, v120, v168
	v_mul_f32_e32 v121, v121, v169
	v_mul_f32_e32 v122, v122, v144
	v_mul_f32_e32 v123, v123, v144
	v_mul_f32_e32 v124, v124, v144
	v_mul_f32_e32 v125, v125, v144
	v_mul_f32_e32 v126, v126, v144
	v_mul_f32_e32 v127, v127, v144
	v_mul_f32_e32 v128, v128, v144
	v_mul_f32_e32 v129, v129, v144
	global_store_dwordx4 v[84:85], v[86:89], off
	v_mul_f32_e32 v122, v122, v145
	v_mul_f32_e32 v123, v123, v146
	v_cvt_pk_bf16_f32 v86, v114, v115
	v_cvt_pk_bf16_f32 v87, v116, v117
	v_cvt_pk_bf16_f32 v88, v118, v119
	v_cvt_pk_bf16_f32 v89, v120, v121
	v_mul_f32_e32 v124, v124, v148
	v_mul_f32_e32 v125, v125, v149
	v_mul_f32_e32 v126, v126, v150
	v_mul_f32_e32 v127, v127, v151
	v_mul_f32_e32 v128, v128, v152
	v_mul_f32_e32 v129, v129, v153
	v_mul_f32_e32 v130, v130, v144
	v_mul_f32_e32 v131, v131, v144
	v_mul_f32_e32 v132, v132, v144
	v_mul_f32_e32 v133, v133, v144
	v_mul_f32_e32 v134, v134, v144
	v_mul_f32_e32 v135, v135, v144
	v_mul_f32_e32 v136, v136, v144
	v_mul_f32_e32 v137, v137, v144
	global_store_dwordx4 v[84:85], v[86:89], off offset:16
	v_mul_f32_e32 v130, v130, v154
	v_mul_f32_e32 v131, v131, v155
	v_cvt_pk_bf16_f32 v86, v122, v123
	v_cvt_pk_bf16_f32 v87, v124, v125
	v_cvt_pk_bf16_f32 v88, v126, v127
	v_cvt_pk_bf16_f32 v89, v128, v129
	v_mul_f32_e32 v132, v132, v156
	v_mul_f32_e32 v133, v133, v157
	v_mul_f32_e32 v134, v134, v158
	v_mul_f32_e32 v135, v135, v159
	v_mul_f32_e32 v136, v136, v160
	v_mul_f32_e32 v137, v137, v161
	global_store_dwordx4 v[84:85], v[86:89], off offset:32
	v_pk_mul_f32 v[92:93], v[144:145], v[138:139] op_sel_hi:[0,1]
	v_mov_b32_e32 v90, v10
	v_cvt_pk_bf16_f32 v86, v130, v131
	v_cvt_pk_bf16_f32 v87, v132, v133
	v_cvt_pk_bf16_f32 v88, v134, v135
	v_cvt_pk_bf16_f32 v89, v136, v137
	global_store_dwordx4 v[84:85], v[86:89], off offset:48
	flat_load_dwordx4 v[114:117], v[142:143] offset:512
	flat_load_dwordx4 v[118:121], v[142:143] offset:640
	flat_load_dwordx4 v[122:125], v[142:143] offset:528
	flat_load_dwordx4 v[126:129], v[142:143] offset:656
	v_mov_b32_e32 v91, v14
	v_pk_mul_f32 v[94:95], v[144:145], v[94:95] op_sel_hi:[0,1]
	v_mov_b32_e32 v88, v12
	v_mov_b32_e32 v89, v16
	v_pk_mul_f32 v[106:107], v[144:145], v[106:107] op_sel_hi:[0,1]
	v_pk_mul_f32 v[96:97], v[144:145], v[96:97] op_sel_hi:[0,1]
	v_mov_b32_e32 v86, v2
	v_mov_b32_e32 v87, v6
	v_pk_mul_f32 v[104:105], v[144:145], v[104:105] op_sel_hi:[0,1]
	v_pk_mul_f32 v[98:99], v[144:145], v[98:99] op_sel_hi:[0,1]
	v_mov_b32_e32 v84, v4
	v_mov_b32_e32 v85, v8
	v_pk_mul_f32 v[102:103], v[144:145], v[102:103] op_sel_hi:[0,1]
	s_waitcnt vmcnt(0) lgkmcnt(0)
	v_mov_b32_e32 v130, v114
	v_mov_b32_e32 v131, v118
	v_pk_mul_f32 v[130:131], v[92:93], v[130:131]
	v_mov_b32_e32 v118, v115
	v_pk_mul_f32 v[92:93], v[90:91], v[130:131]
	s_nop 0
	v_sub_f32_e32 v132, v92, v93
	v_mov_b32_e32 v92, v14
	v_mov_b32_e32 v93, v10
	v_pk_mul_f32 v[130:131], v[92:93], v[130:131]
	v_mov_b32_e32 v14, v11
	v_add_f32_e32 v133, v130, v131
	v_pk_mul_f32 v[130:131], v[144:145], v[140:141] op_sel_hi:[0,1]
	v_pk_mul_f32 v[114:115], v[130:131], v[118:119]
	v_mov_b32_e32 v10, v15
	v_pk_mul_f32 v[118:119], v[14:15], v[114:115]
	v_pk_mul_f32 v[114:115], v[10:11], v[114:115]
	v_sub_f32_e32 v118, v118, v119
	v_add_f32_e32 v119, v114, v115
	v_mov_b32_e32 v114, v116
	v_mov_b32_e32 v115, v120
	v_pk_mul_f32 v[114:115], v[94:95], v[114:115]
	v_mov_b32_e32 v120, v117
	v_pk_mul_f32 v[94:95], v[88:89], v[114:115]
	v_pk_mul_f32 v[106:107], v[106:107], v[120:121]
	v_sub_f32_e32 v116, v94, v95
	v_mov_b32_e32 v94, v16
	v_mov_b32_e32 v95, v12
	v_pk_mul_f32 v[114:115], v[94:95], v[114:115]
	v_mov_b32_e32 v16, v13
	v_mov_b32_e32 v12, v17
	v_add_f32_e32 v130, v114, v115
	v_pk_mul_f32 v[114:115], v[16:17], v[106:107]
	v_pk_mul_f32 v[106:107], v[12:13], v[106:107]
	v_sub_f32_e32 v114, v114, v115
	v_add_f32_e32 v115, v106, v107
	v_mov_b32_e32 v106, v122
	v_mov_b32_e32 v107, v126
	v_pk_mul_f32 v[106:107], v[96:97], v[106:107]
	v_mov_b32_e32 v126, v123
	v_pk_mul_f32 v[96:97], v[86:87], v[106:107]
	v_pk_mul_f32 v[104:105], v[104:105], v[126:127]
	v_sub_f32_e32 v117, v96, v97
	v_mov_b32_e32 v96, v6
	v_mov_b32_e32 v97, v2
	v_pk_mul_f32 v[106:107], v[96:97], v[106:107]
	v_mov_b32_e32 v6, v3
	v_mov_b32_e32 v2, v7
	v_add_f32_e32 v120, v106, v107
	v_pk_mul_f32 v[106:107], v[6:7], v[104:105]
	v_pk_mul_f32 v[104:105], v[2:3], v[104:105]
	v_sub_f32_e32 v106, v106, v107
	v_add_f32_e32 v107, v104, v105
	v_mov_b32_e32 v104, v124
	v_mov_b32_e32 v105, v128
	v_pk_mul_f32 v[104:105], v[98:99], v[104:105]
	v_mov_b32_e32 v128, v125
	v_pk_mul_f32 v[98:99], v[84:85], v[104:105]
	v_pk_mul_f32 v[102:103], v[102:103], v[128:129]
	v_sub_f32_e32 v121, v98, v99
	v_mov_b32_e32 v98, v8
	v_mov_b32_e32 v99, v4
	v_pk_mul_f32 v[104:105], v[98:99], v[104:105]
	v_mov_b32_e32 v8, v5
	v_add_f32_e32 v122, v104, v105
	v_pk_mul_f32 v[104:105], v[8:9], v[102:103]
	v_mov_b32_e32 v4, v9
	v_sub_f32_e32 v105, v104, v105
	v_pk_mul_f32 v[102:103], v[4:5], v[102:103]
	s_nop 0
	v_add_f32_e32 v123, v102, v103
	v_cvt_pk_bf16_f32 v102, v132, v118
	v_cvt_pk_bf16_f32 v103, v116, v114
	v_cvt_pk_bf16_f32 v104, v117, v106
	v_cvt_pk_bf16_f32 v105, v121, v105
	global_store_dwordx4 v[100:101], v[102:105], off
	s_nop 1
	v_cvt_pk_bf16_f32 v102, v133, v119
	v_cvt_pk_bf16_f32 v103, v130, v115
	v_cvt_pk_bf16_f32 v104, v120, v107
	v_cvt_pk_bf16_f32 v105, v122, v123
	global_store_dwordx4 v[100:101], v[102:105], off offset:64
	v_and_b32_e32 v146, 0xffff0000, v54
	v_lshlrev_b32_e32 v148, 16, v54
	v_mul_f32_e32 v185, v146, v146
	v_lshlrev_b32_e32 v145, 16, v55
	v_fmac_f32_e32 v185, v148, v148
	v_and_b32_e32 v144, 0xffff0000, v55
	v_fmac_f32_e32 v185, v145, v145
	v_lshlrev_b32_e32 v152, 16, v56
	v_fmac_f32_e32 v185, v144, v144
	v_and_b32_e32 v151, 0xffff0000, v56
	v_fmac_f32_e32 v185, v152, v152
	v_lshlrev_b32_e32 v150, 16, v57
	v_fmac_f32_e32 v185, v151, v151
	v_and_b32_e32 v149, 0xffff0000, v57
	v_fmac_f32_e32 v185, v150, v150
	v_lshlrev_b32_e32 v139, 16, v50
	v_fmac_f32_e32 v185, v149, v149
	v_and_b32_e32 v158, 0xffff0000, v30
	v_lshlrev_b32_e32 v156, 16, v31
	v_and_b32_e32 v155, 0xffff0000, v31
	v_lshlrev_b32_e32 v154, 16, v32
	v_and_b32_e32 v153, 0xffff0000, v32
	v_and_b32_e32 v106, 0xffff0000, v33
	v_lshlrev_b32_e32 v107, 16, v33
	v_and_b32_e32 v31, 0xffff0000, v58
	v_lshlrev_b32_e32 v33, 16, v59
	v_lshlrev_b32_e32 v32, 16, v58
	v_and_b32_e32 v138, 0xffff0000, v50
	v_fmac_f32_e32 v185, v139, v139
	v_lshlrev_b32_e32 v157, 16, v30
	v_and_b32_e32 v30, 0xffff0000, v26
	v_lshlrev_b32_e32 v101, 16, v27
	v_lshlrev_b32_e32 v100, 16, v26
	v_lshlrev_b32_e32 v103, 16, v28
	v_and_b32_e32 v102, 0xffff0000, v27
	v_lshlrev_b32_e32 v27, 16, v60
	v_lshlrev_b32_e32 v105, 16, v29
	v_and_b32_e32 v104, 0xffff0000, v28
	v_and_b32_e32 v58, 0xffff0000, v60
	v_and_b32_e32 v60, 0xffff0000, v29
	v_lshlrev_b32_e32 v137, 16, v51
	v_lshlrev_b32_e32 v115, 16, v46
	v_and_b32_e32 v114, 0xffff0000, v46
	v_lshlrev_b32_e32 v57, 16, v47
	v_and_b32_e32 v56, 0xffff0000, v47
	v_lshlrev_b32_e32 v47, 16, v40
	v_and_b32_e32 v46, 0xffff0000, v40
	v_and_b32_e32 v28, 0xffff0000, v41
	v_lshlrev_b32_e32 v29, 16, v41
	v_mul_f32_e32 v184, v158, v158
	v_pk_mul_f32 v[40:41], v[106:107], v[106:107]
	v_mul_f32_e32 v106, v31, v31
	v_pk_mul_f32 v[166:167], v[32:33], v[32:33]
	v_fmac_f32_e32 v185, v138, v138
	v_and_b32_e32 v26, 0xffff0000, v59
	v_and_b32_e32 v136, 0xffff0000, v51
	v_lshlrev_b32_e32 v123, 16, v18
	v_and_b32_e32 v122, 0xffff0000, v18
	v_lshlrev_b32_e32 v121, 16, v19
	v_and_b32_e32 v120, 0xffff0000, v19
	v_lshlrev_b32_e32 v127, 16, v20
	v_and_b32_e32 v126, 0xffff0000, v20
	v_lshlrev_b32_e32 v125, 16, v21
	v_and_b32_e32 v124, 0xffff0000, v21
	v_and_b32_e32 v18, 0xffff0000, v34
	v_lshlrev_b32_e32 v19, 16, v34
	v_and_b32_e32 v20, 0xffff0000, v35
	v_lshlrev_b32_e32 v21, 16, v35
	v_lshl_add_u64 v[34:35], s[18:19], 0, v[80:81]
	v_fmac_f32_e32 v184, v157, v157
	v_pk_fma_f32 v[106:107], v[30:31], v[30:31], v[106:107] op_sel_hi:[1,1,0]
	v_pk_fma_f32 v[166:167], v[100:101], v[100:101], v[166:167]
	v_fmac_f32_e32 v185, v137, v137
	v_lshlrev_b32_e32 v143, 16, v52
	v_pk_mul_f32 v[168:169], v[26:27], v[26:27]
	v_mov_b32_e32 v158, v190
	v_mov_b32_e32 v159, v191
	v_mov_b32_e32 v160, v192
	v_mov_b32_e32 v161, v193
	v_mov_b32_e32 v162, v194
	v_mov_b32_e32 v163, v195
	v_mov_b32_e32 v164, v196
	v_mov_b32_e32 v165, v197
	v_fmac_f32_e32 v184, v156, v156
	v_pk_add_f32 v[106:107], v[166:167], v[106:107]
	v_fmac_f32_e32 v185, v136, v136
	v_lshlrev_b32_e32 v59, 16, v61
	v_and_b32_e32 v142, 0xffff0000, v52
	v_pk_fma_f32 v[168:169], v[102:103], v[102:103], v[168:169]
	v_fmac_f32_e32 v184, v155, v155
	v_pk_add_f32 v[106:107], v[166:167], v[106:107] op_sel:[1,0] op_sel_hi:[0,1]
	v_fmac_f32_e32 v185, v143, v143
	v_lshlrev_b32_e32 v141, 16, v53
	v_pk_mul_f32 v[170:171], v[58:59], v[58:59]
	v_fmac_f32_e32 v184, v154, v154
	v_pk_add_f32 v[106:107], v[168:169], v[106:107]
	v_fmac_f32_e32 v185, v142, v142
	v_and_b32_e32 v140, 0xffff0000, v53
	v_pk_fma_f32 v[170:171], v[104:105], v[104:105], v[170:171]
	v_fmac_f32_e32 v184, v153, v153
	v_pk_add_f32 v[106:107], v[168:169], v[106:107] op_sel:[1,0] op_sel_hi:[0,1]
	v_fmac_f32_e32 v185, v141, v141
	v_lshlrev_b32_e32 v131, 16, v22
	v_add_f32_e32 v41, v41, v184
	v_pk_add_f32 v[106:107], v[170:171], v[106:107]
	v_fmac_f32_e32 v185, v140, v140
	v_and_b32_e32 v130, 0xffff0000, v22
	v_add_f32_e32 v153, v40, v41
	v_pk_add_f32 v[40:41], v[170:171], v[106:107] op_sel:[1,0] op_sel_hi:[0,1]
	v_fmac_f32_e32 v185, v131, v131
	v_lshlrev_b32_e32 v129, 16, v23
	ds_bpermute_b32 v41, v63, v153
	v_fmac_f32_e32 v185, v130, v130
	v_and_b32_e32 v128, 0xffff0000, v23
	v_fmac_f32_e32 v185, v129, v129
	v_lshlrev_b32_e32 v135, 16, v24
	v_fmac_f32_e32 v185, v128, v128
	v_and_b32_e32 v134, 0xffff0000, v24
	v_fmac_f32_e32 v185, v135, v135
	v_lshlrev_b32_e32 v133, 16, v25
	v_fmac_f32_e32 v185, v134, v134
	v_and_b32_e32 v132, 0xffff0000, v25
	s_waitcnt lgkmcnt(0)
	v_add_f32_e32 v41, v153, v41
	v_fmac_f32_e32 v185, v133, v133
	ds_bpermute_b32 v106, v108, v41
	v_fmac_f32_e32 v185, v132, v132
	v_fmac_f32_e32 v185, v123, v123
	v_fmac_f32_e32 v185, v122, v122
	v_fmac_f32_e32 v185, v121, v121
	v_fmac_f32_e32 v185, v120, v120
	s_waitcnt lgkmcnt(0)
	v_add_f32_e32 v41, v41, v106
	v_fmac_f32_e32 v185, v127, v127
	ds_bpermute_b32 v106, v109, v41
	v_fmac_f32_e32 v185, v126, v126
	v_fmac_f32_e32 v185, v125, v125
	v_fmac_f32_e32 v185, v124, v124
	v_fmac_f32_e32 v185, v115, v115
	v_fmac_f32_e32 v185, v114, v114
	s_waitcnt lgkmcnt(0)
	v_add_f32_e32 v41, v41, v106
	v_fmac_f32_e32 v185, v57, v57
	v_lshlrev_b32_e32 v119, 16, v48
	ds_bpermute_b32 v106, v110, v41
	v_fmac_f32_e32 v185, v56, v56
	v_and_b32_e32 v118, 0xffff0000, v48
	v_fmac_f32_e32 v185, v119, v119
	v_lshlrev_b32_e32 v117, 16, v49
	v_fmac_f32_e32 v185, v118, v118
	v_and_b32_e32 v116, 0xffff0000, v49
	v_fmac_f32_e32 v185, v117, v117
	v_lshlrev_b32_e32 v51, 16, v42
	v_fmac_f32_e32 v185, v116, v116
	v_and_b32_e32 v50, 0xffff0000, v42
	s_waitcnt lgkmcnt(0)
	v_add_f32_e32 v41, v41, v106
	v_fmac_f32_e32 v185, v51, v51
	v_lshlrev_b32_e32 v49, 16, v43
	ds_bpermute_b32 v106, v111, v41
	v_fmac_f32_e32 v185, v50, v50
	v_and_b32_e32 v48, 0xffff0000, v43
	v_fmac_f32_e32 v185, v49, v49
	v_lshlrev_b32_e32 v55, 16, v44
	v_fmac_f32_e32 v185, v48, v48
	v_and_b32_e32 v54, 0xffff0000, v44
	v_fmac_f32_e32 v185, v55, v55
	v_lshlrev_b32_e32 v53, 16, v45
	v_fmac_f32_e32 v185, v54, v54
	v_and_b32_e32 v52, 0xffff0000, v45
	s_waitcnt lgkmcnt(0)
	v_add_f32_e32 v41, v41, v106
	v_fmac_f32_e32 v185, v53, v53
	v_lshlrev_b32_e32 v45, 16, v38
	ds_bpermute_b32 v106, v112, v41
	v_fmac_f32_e32 v185, v52, v52
	v_and_b32_e32 v44, 0xffff0000, v38
	v_fmac_f32_e32 v185, v45, v45
	v_lshlrev_b32_e32 v43, 16, v39
	v_fmac_f32_e32 v185, v44, v44
	v_and_b32_e32 v42, 0xffff0000, v39
	v_fmac_f32_e32 v185, v43, v43
	v_fmac_f32_e32 v185, v42, v42
	s_waitcnt lgkmcnt(0)
	v_add_f32_e32 v41, v41, v106
	v_fmac_f32_e32 v185, v47, v47
	v_pk_mul_f32 v[172:173], v[28:29], v[28:29]
	v_fmamk_f32 v41, v41, 0x3b000000, v113
	v_fmac_f32_e32 v185, v46, v46
	v_rsq_f32_e32 v153, v41
	v_add_f32_e32 v41, v173, v185
	v_pk_mul_f32 v[174:175], v[18:19], v[18:19]
	v_add_f32_e32 v41, v172, v41
	v_add_f32_e32 v41, v175, v41
	v_pk_mul_f32 v[176:177], v[20:21], v[20:21]
	v_add_f32_e32 v41, v174, v41
	v_and_b32_e32 v22, 0xffff0000, v36
	v_lshlrev_b32_e32 v23, 16, v36
	v_add_f32_e32 v41, v177, v41
	v_pk_mul_f32 v[178:179], v[22:23], v[22:23]
	v_add_f32_e32 v41, v176, v41
	v_and_b32_e32 v24, 0xffff0000, v37
	v_lshlrev_b32_e32 v25, 16, v37
	v_add_f32_e32 v41, v179, v41
	v_and_b32_e32 v61, 0xffff0000, v61
	v_pk_mul_f32 v[180:181], v[24:25], v[24:25]
	v_add_f32_e32 v41, v178, v41
	v_mul_f32_e32 v182, v61, v61
	v_add_f32_e32 v41, v181, v41
	v_pk_fma_f32 v[182:183], v[60:61], v[60:61], v[182:183] op_sel_hi:[1,1,0]
	v_add_f32_e32 v41, v180, v41
	v_cndmask_b32_e64 v183, 0, v41, s[0:1]
	ds_bpermute_b32 v106, v63, v183
	s_waitcnt vmcnt(0)
	v_cndmask_b32_e64 v155, v159, 1.0, s[4:5]
	v_cndmask_b32_e64 v156, v158, 1.0, s[4:5]
	v_cndmask_b32_e64 v159, v163, 1.0, s[4:5]
	v_cndmask_b32_e64 v154, v160, 1.0, s[4:5]
	s_waitcnt lgkmcnt(0)
	v_mov_b32_e32 v41, v106
	v_pk_add_f32 v[40:41], v[182:183], v[40:41]
	ds_bpermute_b32 v106, v63, v40
	ds_bpermute_b32 v107, v108, v41
	v_cndmask_b32_e64 v157, v165, 1.0, s[4:5]
	v_cndmask_b32_e64 v158, v164, 1.0, s[4:5]
	v_cndmask_b32_e64 v160, v162, 1.0, s[4:5]
	v_lshl_add_u64 v[36:37], s[18:19], 0, v[78:79]
	s_waitcnt lgkmcnt(0)
	v_pk_add_f32 v[40:41], v[40:41], v[106:107]
	ds_bpermute_b32 v106, v108, v40
	v_mul_f32_e32 v41, v41, v153
	v_cndmask_b32_e64 v107, v161, 1.0, s[4:5]
	v_lshl_add_u64 v[38:39], s[96:97], 0, v[76:77]
	s_add_i32 s31, s31, s46
	s_waitcnt lgkmcnt(0)
	v_add_f32_e32 v40, v40, v106
	v_fmac_f32_e32 v40, v153, v41
	v_fmamk_f32 v40, v40, 0x3baaaaab, v113
	v_rsq_f32_e32 v40, v40
	s_add_i32 s26, s26, s27
	v_add_co_u32_e32 v38, vcc, s28, v38
	v_mul_f32_e32 v41, v153, v40
	v_cndmask_b32_e64 v41, v153, v41, s[0:1]
	v_mul_f32_e32 v106, v156, v41
	v_mul_f32_e32 v156, v159, v41
	v_mul_f32_e32 v153, v160, v41
	v_mul_f32_e32 v155, v155, v41
	v_mul_f32_e32 v154, v154, v41
	v_mul_f32_e32 v158, v158, v41
	v_mul_f32_e32 v107, v107, v41
	v_mul_f32_e32 v157, v157, v41
	v_mul_f32_e32 v151, v156, v151
	v_mul_f32_e32 v106, v106, v148
	v_mul_f32_e32 v152, v153, v152
	v_mul_f32_e32 v146, v155, v146
	v_mul_f32_e32 v145, v154, v145
	v_mul_f32_e32 v153, v158, v150
	v_mul_f32_e32 v107, v107, v144
	v_mul_f32_e32 v144, v157, v149
	v_cvt_pk_bf16_f32 v148, v106, v146
	v_cvt_pk_bf16_f32 v149, v145, v107
	v_cvt_pk_bf16_f32 v150, v152, v151
	v_cvt_pk_bf16_f32 v151, v153, v144
	global_store_dwordx4 v[82:83], v[148:151], off
	s_nop 1
	v_mov_b32_e32 v148, v198
	v_mov_b32_e32 v149, v199
	v_mov_b32_e32 v150, v200
	v_mov_b32_e32 v151, v201
	s_nop 0
	v_mov_b32_e32 v152, v202
	v_mov_b32_e32 v153, v203
	v_mov_b32_e32 v154, v204
	v_mov_b32_e32 v155, v205
	v_lshl_add_u64 v[66:67], v[66:67], 0, s[6:7]
	v_lshl_add_u64 v[68:69], v[68:69], 0, s[8:9]
	v_lshl_add_u64 v[70:71], v[70:71], 0, s[8:9]
	v_lshl_add_u64 v[72:73], v[72:73], 0, s[10:11]
	v_lshl_add_u64 v[74:75], v[74:75], 0, s[10:11]
	v_lshl_add_u64 v[76:77], v[76:77], 0, s[10:11]
	v_addc_co_u32_e32 v39, vcc, 0, v39, vcc
	s_cmp_lt_i32 s31, 0x8000
	s_waitcnt lgkmcnt(0)
	v_cndmask_b32_e64 v144, v149, 1.0, s[4:5]
	v_cndmask_b32_e64 v145, v148, 1.0, s[4:5]
	v_cndmask_b32_e64 v106, v151, 1.0, s[4:5]
	v_cndmask_b32_e64 v107, v150, 1.0, s[4:5]
	v_cndmask_b32_e64 v146, v155, 1.0, s[4:5]
	v_cndmask_b32_e64 v148, v154, 1.0, s[4:5]
	v_cndmask_b32_e64 v149, v153, 1.0, s[4:5]
	v_cndmask_b32_e64 v150, v152, 1.0, s[4:5]
	v_mul_f32_e32 v145, v145, v41
	v_mul_f32_e32 v144, v144, v41
	v_mul_f32_e32 v150, v41, v150
	v_mul_f32_e32 v149, v41, v149
	v_mul_f32_e32 v107, v107, v41
	v_mul_f32_e32 v148, v41, v148
	v_mul_f32_e32 v106, v106, v41
	v_mul_f32_e32 v146, v41, v146
	v_mul_f32_e32 v139, v145, v139
	v_mul_f32_e32 v138, v144, v138
	v_mul_f32_e32 v143, v150, v143
	v_mul_f32_e32 v142, v149, v142
	v_mul_f32_e32 v107, v107, v137
	v_mul_f32_e32 v141, v148, v141
	v_mul_f32_e32 v106, v106, v136
	v_mul_f32_e32 v140, v146, v140
	v_cvt_pk_bf16_f32 v136, v139, v138
	v_cvt_pk_bf16_f32 v137, v107, v106
	v_cvt_pk_bf16_f32 v138, v143, v142
	v_cvt_pk_bf16_f32 v139, v141, v140
	global_store_dwordx4 v[82:83], v[136:139], off offset:16
	s_nop 1
	v_mov_b32_e32 v136, v206
	v_mov_b32_e32 v137, v207
	v_mov_b32_e32 v138, v208
	v_mov_b32_e32 v139, v209
	s_nop 0
	v_mov_b32_e32 v140, v210
	v_mov_b32_e32 v141, v211
	v_mov_b32_e32 v142, v212
	v_mov_b32_e32 v143, v213
	s_waitcnt lgkmcnt(0)
	v_cndmask_b32_e64 v137, v137, 1.0, s[4:5]
	v_cndmask_b32_e64 v136, v136, 1.0, s[4:5]
	v_cndmask_b32_e64 v106, v139, 1.0, s[4:5]
	v_cndmask_b32_e64 v107, v138, 1.0, s[4:5]
	v_cndmask_b32_e64 v138, v143, 1.0, s[4:5]
	v_cndmask_b32_e64 v139, v142, 1.0, s[4:5]
	v_cndmask_b32_e64 v141, v141, 1.0, s[4:5]
	v_cndmask_b32_e64 v140, v140, 1.0, s[4:5]
	v_mul_f32_e32 v136, v41, v136
	v_mul_f32_e32 v137, v41, v137
	v_mul_f32_e32 v140, v41, v140
	v_mul_f32_e32 v141, v41, v141
	v_mul_f32_e32 v107, v41, v107
	v_mul_f32_e32 v139, v41, v139
	v_mul_f32_e32 v106, v41, v106
	v_mul_f32_e32 v138, v41, v138
	v_mul_f32_e32 v131, v136, v131
	v_mul_f32_e32 v130, v137, v130
	v_mul_f32_e32 v135, v140, v135
	v_mul_f32_e32 v134, v141, v134
	v_mul_f32_e32 v107, v107, v129
	v_mul_f32_e32 v133, v139, v133
	v_mul_f32_e32 v106, v106, v128
	v_mul_f32_e32 v132, v138, v132
	v_cvt_pk_bf16_f32 v128, v131, v130
	v_cvt_pk_bf16_f32 v129, v107, v106
	v_cvt_pk_bf16_f32 v130, v135, v134
	v_cvt_pk_bf16_f32 v131, v133, v132
	global_store_dwordx4 v[82:83], v[128:131], off offset:32
	s_nop 1
	v_mov_b32_e32 v128, v214
	v_mov_b32_e32 v129, v215
	v_mov_b32_e32 v130, v216
	v_mov_b32_e32 v131, v217
	s_nop 0
	v_mov_b32_e32 v132, v218
	v_mov_b32_e32 v133, v219
	v_mov_b32_e32 v134, v220
	v_mov_b32_e32 v135, v221
	s_waitcnt lgkmcnt(0)
	v_cndmask_b32_e64 v129, v129, 1.0, s[4:5]
	v_cndmask_b32_e64 v128, v128, 1.0, s[4:5]
	v_cndmask_b32_e64 v106, v131, 1.0, s[4:5]
	v_cndmask_b32_e64 v107, v130, 1.0, s[4:5]
	v_cndmask_b32_e64 v130, v135, 1.0, s[4:5]
	v_cndmask_b32_e64 v131, v134, 1.0, s[4:5]
	v_cndmask_b32_e64 v133, v133, 1.0, s[4:5]
	v_cndmask_b32_e64 v132, v132, 1.0, s[4:5]
	v_mul_f32_e32 v128, v41, v128
	v_mul_f32_e32 v129, v41, v129
	v_mul_f32_e32 v132, v41, v132
	v_mul_f32_e32 v133, v41, v133
	v_mul_f32_e32 v107, v41, v107
	v_mul_f32_e32 v131, v41, v131
	v_mul_f32_e32 v106, v41, v106
	v_mul_f32_e32 v130, v41, v130
	v_mul_f32_e32 v123, v128, v123
	v_mul_f32_e32 v122, v129, v122
	v_mul_f32_e32 v127, v132, v127
	v_mul_f32_e32 v126, v133, v126
	v_mul_f32_e32 v107, v107, v121
	v_mul_f32_e32 v125, v131, v125
	v_mul_f32_e32 v106, v106, v120
	v_mul_f32_e32 v124, v130, v124
	v_cvt_pk_bf16_f32 v120, v123, v122
	v_cvt_pk_bf16_f32 v121, v107, v106
	v_cvt_pk_bf16_f32 v122, v127, v126
	v_cvt_pk_bf16_f32 v123, v125, v124
	global_store_dwordx4 v[82:83], v[120:123], off offset:48
	s_nop 1
	ds_read_b128 v[120:123], v188
	s_nop 0
	ds_read_b128 v[124:127], v188 offset:1024
	s_waitcnt lgkmcnt(0)
	v_cndmask_b32_e64 v121, v121, 1.0, s[4:5]
	v_cndmask_b32_e64 v120, v120, 1.0, s[4:5]
	v_cndmask_b32_e64 v106, v123, 1.0, s[4:5]
	v_cndmask_b32_e64 v107, v122, 1.0, s[4:5]
	v_cndmask_b32_e64 v122, v127, 1.0, s[4:5]
	v_cndmask_b32_e64 v123, v126, 1.0, s[4:5]
	v_cndmask_b32_e64 v125, v125, 1.0, s[4:5]
	v_cndmask_b32_e64 v124, v124, 1.0, s[4:5]
	v_mul_f32_e32 v120, v41, v120
	v_mul_f32_e32 v121, v41, v121
	v_mul_f32_e32 v124, v41, v124
	v_mul_f32_e32 v125, v41, v125
	v_mul_f32_e32 v107, v41, v107
	v_mul_f32_e32 v123, v41, v123
	v_mul_f32_e32 v106, v41, v106
	v_mul_f32_e32 v122, v41, v122
	v_mul_f32_e32 v115, v120, v115
	v_mul_f32_e32 v114, v121, v114
	v_mul_f32_e32 v119, v124, v119
	v_mul_f32_e32 v118, v125, v118
	v_mul_f32_e32 v57, v107, v57
	v_mul_f32_e32 v107, v123, v117
	v_mul_f32_e32 v56, v106, v56
	v_mul_f32_e32 v106, v122, v116
	v_cvt_pk_bf16_f32 v114, v115, v114
	v_cvt_pk_bf16_f32 v115, v57, v56
	v_cvt_pk_bf16_f32 v116, v119, v118
	v_cvt_pk_bf16_f32 v117, v107, v106
	global_store_dwordx4 v[82:83], v[114:117], off offset:64
	s_nop 1
	ds_read_b128 v[114:117], v188 offset:2048
	s_nop 0
	ds_read_b128 v[118:121], v188 offset:3072
	s_waitcnt lgkmcnt(0)
	v_cndmask_b32_e64 v57, v116, 1.0, s[4:5]
	v_cndmask_b32_e64 v106, v115, 1.0, s[4:5]
	v_cndmask_b32_e64 v107, v114, 1.0, s[4:5]
	v_cndmask_b32_e64 v56, v117, 1.0, s[4:5]
	v_cndmask_b32_e64 v114, v121, 1.0, s[4:5]
	v_cndmask_b32_e64 v115, v120, 1.0, s[4:5]
	v_cndmask_b32_e64 v116, v119, 1.0, s[4:5]
	v_cndmask_b32_e64 v117, v118, 1.0, s[4:5]
	v_mul_f32_e32 v107, v41, v107
	v_mul_f32_e32 v106, v41, v106
	v_mul_f32_e32 v57, v41, v57
	v_mul_f32_e32 v117, v41, v117
	v_mul_f32_e32 v116, v41, v116
	v_mul_f32_e32 v115, v41, v115
	v_mul_f32_e32 v56, v41, v56
	v_mul_f32_e32 v114, v41, v114
	v_mul_f32_e32 v51, v107, v51
	v_mul_f32_e32 v50, v106, v50
	v_mul_f32_e32 v49, v57, v49
	v_mul_f32_e32 v55, v117, v55
	v_mul_f32_e32 v54, v116, v54
	v_mul_f32_e32 v53, v115, v53
	v_mul_f32_e32 v56, v56, v48
	v_mul_f32_e32 v52, v114, v52
	v_cvt_pk_bf16_f32 v48, v51, v50
	v_cvt_pk_bf16_f32 v49, v49, v56
	v_cvt_pk_bf16_f32 v50, v55, v54
	v_cvt_pk_bf16_f32 v51, v53, v52
	global_store_dwordx4 v[82:83], v[48:51], off offset:80
	s_nop 1
	ds_read_b128 v[48:51], v188 offset:4096
	s_nop 0
	ds_read_b128 v[52:55], v188 offset:5120
	s_waitcnt lgkmcnt(0)
	v_cndmask_b32_e64 v50, v50, 1.0, s[4:5]
	v_cndmask_b32_e64 v49, v49, 1.0, s[4:5]
	v_cndmask_b32_e64 v48, v48, 1.0, s[4:5]
	v_cndmask_b32_e64 v51, v51, 1.0, s[4:5]
	v_cndmask_b32_e64 v55, v55, 1.0, s[4:5]
	v_cndmask_b32_e64 v54, v54, 1.0, s[4:5]
	v_cndmask_b32_e64 v53, v53, 1.0, s[4:5]
	v_cndmask_b32_e64 v52, v52, 1.0, s[4:5]
	v_mul_f32_e32 v48, v41, v48
	v_mul_f32_e32 v49, v41, v49
	v_mul_f32_e32 v50, v41, v50
	v_mul_f32_e32 v52, v41, v52
	v_mul_f32_e32 v53, v41, v53
	v_mul_f32_e32 v54, v41, v54
	v_mul_f32_e32 v51, v41, v51
	v_mul_f32_e32 v55, v41, v55
	v_mul_f32_e32 v45, v48, v45
	v_mul_f32_e32 v44, v49, v44
	v_mul_f32_e32 v43, v50, v43
	v_mul_f32_e32 v47, v52, v47
	v_mul_f32_e32 v46, v53, v46
	v_mul_f32_e32 v29, v54, v29
	v_mul_f32_e32 v48, v51, v42
	v_mul_f32_e32 v28, v55, v28
	v_cvt_pk_bf16_f32 v42, v45, v44
	v_cvt_pk_bf16_f32 v43, v43, v48
	v_cvt_pk_bf16_f32 v44, v47, v46
	v_cvt_pk_bf16_f32 v45, v29, v28
	global_store_dwordx4 v[82:83], v[42:45], off offset:96
	s_nop 1
	ds_read_b128 v[42:45], v188 offset:6144
	s_nop 0
	ds_read_b128 v[46:49], v188 offset:7168
	s_waitcnt lgkmcnt(0)
	v_cndmask_b32_e64 v28, v45, 1.0, s[4:5]
	v_cndmask_b32_e64 v29, v44, 1.0, s[4:5]
	v_cndmask_b32_e64 v34, v43, 1.0, s[4:5]
	v_cndmask_b32_e64 v35, v42, 1.0, s[4:5]
	v_cndmask_b32_e64 v42, v49, 1.0, s[4:5]
	v_cndmask_b32_e64 v43, v48, 1.0, s[4:5]
	v_cndmask_b32_e64 v44, v47, 1.0, s[4:5]
	v_cndmask_b32_e64 v45, v46, 1.0, s[4:5]
	v_mul_f32_e32 v35, v41, v35
	v_mul_f32_e32 v34, v41, v34
	v_mul_f32_e32 v29, v41, v29
	v_mul_f32_e32 v28, v41, v28
	v_mul_f32_e32 v45, v41, v45
	v_mul_f32_e32 v44, v41, v44
	v_mul_f32_e32 v43, v41, v43
	v_mul_f32_e32 v41, v41, v42
	v_mul_f32_e32 v19, v35, v19
	v_mul_f32_e32 v18, v34, v18
	v_mul_f32_e32 v21, v29, v21
	v_mul_f32_e32 v20, v28, v20
	v_mul_f32_e32 v23, v45, v23
	v_mul_f32_e32 v22, v44, v22
	v_mul_f32_e32 v25, v43, v25
	v_mul_f32_e32 v24, v41, v24
	v_cvt_pk_bf16_f32 v18, v19, v18
	v_cvt_pk_bf16_f32 v19, v21, v20
	v_cvt_pk_bf16_f32 v20, v23, v22
	v_cvt_pk_bf16_f32 v21, v25, v24
	global_store_dwordx4 v[82:83], v[18:21], off offset:112
	flat_load_dwordx4 v[18:21], v[36:37] offset:512
	s_nop 0
	flat_load_dwordx4 v[22:25], v[36:37] offset:640
	flat_load_dwordx4 v[42:45], v[36:37] offset:528
	s_nop 0
	flat_load_dwordx4 v[34:37], v[36:37] offset:656
	v_mov_b32_e32 v28, v100
	v_mov_b32_e32 v29, v32
	v_mov_b32_e32 v32, v101
	v_mov_b32_e32 v46, v102
	v_mov_b32_e32 v47, v26
	v_mov_b32_e32 v26, v103
	v_mov_b32_e32 v48, v104
	v_mov_b32_e32 v49, v58
	v_mov_b32_e32 v58, v105
	v_pk_mul_f32 v[28:29], v[40:41], v[28:29] op_sel_hi:[0,1]
	v_pk_mul_f32 v[30:31], v[40:41], v[30:31] op_sel_hi:[0,1]
	v_pk_mul_f32 v[32:33], v[40:41], v[32:33] op_sel_hi:[0,1]
	v_pk_mul_f32 v[46:47], v[40:41], v[46:47] op_sel_hi:[0,1]
	v_pk_mul_f32 v[26:27], v[40:41], v[26:27] op_sel_hi:[0,1]
	v_pk_mul_f32 v[48:49], v[40:41], v[48:49] op_sel_hi:[0,1]
	v_pk_mul_f32 v[50:51], v[40:41], v[58:59] op_sel_hi:[0,1]
	v_pk_mul_f32 v[40:41], v[40:41], v[60:61] op_sel_hi:[0,1]
	s_waitcnt vmcnt(0) lgkmcnt(0)
	v_mov_b32_e32 v52, v18
	v_mov_b32_e32 v53, v22
	v_mov_b32_e32 v22, v19
	v_mov_b32_e32 v18, v20
	v_mov_b32_e32 v19, v24
	v_mov_b32_e32 v24, v21
	v_mov_b32_e32 v20, v42
	v_mov_b32_e32 v21, v34
	v_mov_b32_e32 v34, v43
	v_mov_b32_e32 v42, v44
	v_mov_b32_e32 v43, v36
	v_mov_b32_e32 v36, v45
	v_pk_mul_f32 v[28:29], v[28:29], v[52:53]
	v_pk_mul_f32 v[22:23], v[30:31], v[22:23]
	v_pk_mul_f32 v[18:19], v[32:33], v[18:19]
	v_pk_mul_f32 v[24:25], v[46:47], v[24:25]
	v_pk_mul_f32 v[20:21], v[26:27], v[20:21]
	v_pk_mul_f32 v[26:27], v[48:49], v[34:35]
	v_pk_mul_f32 v[30:31], v[50:51], v[42:43]
	v_pk_mul_f32 v[32:33], v[40:41], v[36:37]
	v_pk_mul_f32 v[34:35], v[90:91], v[28:29]
	v_pk_mul_f32 v[14:15], v[14:15], v[22:23]
	v_pk_mul_f32 v[10:11], v[10:11], v[22:23]
	v_pk_mul_f32 v[22:23], v[88:89], v[18:19]
	v_pk_mul_f32 v[18:19], v[94:95], v[18:19]
	v_pk_mul_f32 v[16:17], v[16:17], v[24:25]
	v_pk_mul_f32 v[12:13], v[12:13], v[24:25]
	v_pk_mul_f32 v[24:25], v[86:87], v[20:21]
	v_pk_mul_f32 v[6:7], v[6:7], v[26:27]
	v_pk_mul_f32 v[2:3], v[2:3], v[26:27]
	v_pk_mul_f32 v[26:27], v[84:85], v[30:31]
	v_pk_mul_f32 v[8:9], v[8:9], v[32:33]
	v_pk_mul_f32 v[4:5], v[4:5], v[32:33]
	v_pk_mul_f32 v[28:29], v[92:93], v[28:29]
	v_pk_mul_f32 v[20:21], v[96:97], v[20:21]
	v_pk_mul_f32 v[30:31], v[98:99], v[30:31]
	v_sub_f32_e32 v32, v34, v35
	v_sub_f32_e32 v14, v14, v15
	v_add_f32_e32 v10, v10, v11
	v_sub_f32_e32 v11, v22, v23
	v_add_f32_e32 v15, v18, v19
	v_sub_f32_e32 v16, v16, v17
	v_add_f32_e32 v12, v12, v13
	v_sub_f32_e32 v13, v24, v25
	v_sub_f32_e32 v6, v6, v7
	v_add_f32_e32 v7, v2, v3
	v_sub_f32_e32 v18, v26, v27
	v_sub_f32_e32 v8, v8, v9
	v_add_f32_e32 v9, v4, v5
	v_cvt_pk_bf16_f32 v2, v32, v14
	v_cvt_pk_bf16_f32 v3, v11, v16
	v_cvt_pk_bf16_f32 v4, v13, v6
	v_cvt_pk_bf16_f32 v5, v18, v8
	v_add_f32_e32 v28, v28, v29
	v_add_f32_e32 v17, v20, v21
	v_add_f32_e32 v19, v30, v31
	global_store_dwordx4 v[38:39], v[2:5], off
	s_nop 1
	v_cvt_pk_bf16_f32 v2, v28, v10
	v_cvt_pk_bf16_f32 v3, v15, v12
	v_cvt_pk_bf16_f32 v4, v17, v7
	v_cvt_pk_bf16_f32 v5, v19, v9
	global_store_dwordx4 v[38:39], v[2:5], off offset:64
	s_cbranch_scc1 .LBB0_275
